# NA step2 loop: all K-fragment reads issued up front, bias reads interleaved, bias table offset folded into loop address registers
# speedup vs baseline: 1.0099x; 1.0028x over previous
; #define LAS __attribute__((address_space(3)))
; __device__ __forceinline__ f32x4 mfma16(bf16x8 a, bf16x8 b, f32x4 c) { return __builtin_amdgcn_mfma_f32_16x16x32_bf16(a, b, c, 0, 0, 0); }
; template <int ND> ...
;     ...
;     __builtin_amdgcn_s_setprio(1);
; #pragma unroll
;     for (int kk = 0; kk < 2; ++kk)
; #pragma unroll
;         for (int u = 0; u < 2 * ND; ++u) {
;             const bf16x8 kf = *(const LAS bf16x8*)(lds + kbase + (key0[u >> 1] + (u & 1) * 16 + fr) * 144 + kk * 64 + fq * 16);
;             sc[u] = mfma16(kf, qf[kk], sc[u]); }
;     __builtin_amdgcn_s_setprio(0);
;     if (loc) {
; #pragma unroll
;         for (int g = 0; g < ND; ++g)
; #pragma unroll
;             for (int i = 0; i < 4; ++i) {
;                 const int ck0 = cst + fq * 4 + i, ck1 = ck0 + 16;
;                 const int rel0 = min(max(ck0 - cq + 15, 0), 30), rel1 = min(max(ck1 - cq + 15, 0), 30);
;                 const bool v0 = (ck0 >= c0w) && (ck0 < c0w + 16), v1 = (ck1 >= c0w) && (ck1 < c0w + 16);
;                 sc[2 * g][i] = v0 ? sc[2 * g][i] + rpb[dr[g] * 31 + rel0] : -INFINITY;
;                 sc[2 * g + 1][i] = v1 ? sc[2 * g + 1][i] + rpb[dr[g] * 31 + rel1] : -INFINITY; }
; __device__ __forceinline__ void na_item(int wv, const Params& p, int l, int it, LAS unsigned char* lds) {
;     ...
;             const int p0 = 5 * ps, lo = max(off, p0), hi = min(off + 8, ps ? 9 : 5);
;             int rel = lo;
;             for (; rel + 1 < hi; rel += 2) { const int key0[2] = {(rel - p0) * 64 + cst, (rel + 1 - p0) * 64 + cst}; const int dr[2] = {(r0 + rel - off) - r + 7, (r0 + rel + 1 - off) - r + 7};
;                 na_step<2>(lds, NB_KLOC, NB_VLOC, 656, key0, true, dr, rpb, qf, fr, fq, lane, cst, cq, c0w, m_run, l_run, O); }
.LBB0_772:
	s_xor_b64 s[50:51], s[88:89], -1
	s_and_b64 vcc, exec, s[14:15]
	s_cbranch_vccnz .LBB0_736
	s_max_i32 s4, s84, s3
	s_and_b64 s[46:47], s[72:73], exec
	s_cselect_b32 s5, 9, 5
	s_min_i32 s46, s95, s5
	s_add_i32 s47, s4, 1
	s_cmp_ge_i32 s47, s46
	s_cbranch_scc1 .LBB0_809
	v_lshl_add_u32 v0, s4, 7, v165
	s_lshl_b32 s5, s3, 7
	v_subrev_u32_e32 v190, s5, v0
	s_mul_i32 s5, s4, 0x2400
	v_or_b32_e32 v0, s5, v104
	s_mul_i32 s72, s3, 0x2400
	v_subrev_u32_e32 v191, s72, v0
	v_add_u32_e32 v0, s5, v158
	s_add_i32 s73, s63, s4
	v_subrev_u32_e32 v210, s72, v0
	v_lshl_add_u32 v0, s4, 6, v145
	s_lshl_b32 s4, s3, 6
	s_mulk_i32 s73, 0x7c
	s_add_i32 s73, s73, 0x1e764
	v_subrev_u32_e32 v0, s4, v0
	v_add_u32_e32 v192, s73, v167
	v_add_u32_e32 v193, s73, v168
	v_add_u32_e32 v194, s73, v169
	v_add_u32_e32 v195, s73, v170
	v_add_u32_e32 v206, s73, v171
	v_add_u32_e32 v207, s73, v172
	v_add_u32_e32 v208, s73, v173
	v_add_u32_e32 v209, s73, v174
	v_lshl_add_u32 v211, v0, 1, v155
.LBB0_775:
	v_add_u32_e32 v2, v166, v191
	v_add_u32_e32 v0, v175, v210
	s_setprio 1
	ds_read_b128 v[96:99], v0
	ds_read_b128 v[92:95], v2
	ds_read_b128 v[84:87], v2 offset:6912
	ds_read_b128 v[88:91], v2 offset:9216
	ds_read_b128 v[198:201], v0 offset:64
	ds_read_b128 v[212:215], v2 offset:64
	ds_read_b128 v[220:223], v2 offset:6976
	ds_read_b128 v[224:227], v2 offset:9280
	ds_read_b32 v3, v192
	ds_read_b32 v234, v193
	ds_read_b32 v235, v194
	ds_read_b32 v248, v195
	ds_read_b32 v249, v206
	ds_read_b32 v250, v207
	ds_read_b32 v251, v208
	s_waitcnt lgkmcnt(11)
	v_mfma_f32_16x16x32_bf16 v[96:99], v[96:99], v[4:7], 0
	v_mfma_f32_16x16x32_bf16 v[92:95], v[92:95], v[4:7], 0
	v_mfma_f32_16x16x32_bf16 v[84:87], v[84:87], v[4:7], 0
	v_mfma_f32_16x16x32_bf16 v[88:91], v[88:91], v[4:7], 0
	ds_read_b32 v219, v209
	s_waitcnt lgkmcnt(10)
	v_mfma_f32_16x16x32_bf16 v[96:99], v[198:201], v[8:11], v[96:99]
	v_mfma_f32_16x16x32_bf16 v[92:95], v[212:215], v[8:11], v[92:95]
	ds_read_b32 v198, v192 offset:124
	ds_read_b32 v199, v193 offset:124
	ds_read_b32 v200, v194 offset:124
	ds_read_b32 v201, v195 offset:124
	ds_read_b32 v212, v206 offset:124
	s_waitcnt lgkmcnt(13)
	v_mfma_f32_16x16x32_bf16 v[84:87], v[220:223], v[8:11], v[84:87]
	v_mfma_f32_16x16x32_bf16 v[88:91], v[224:227], v[8:11], v[88:91]
	s_waitcnt lgkmcnt(5)
	ds_read_b32 v213, v207 offset:124
	ds_read_b32 v214, v208 offset:124
	ds_read_b32 v215, v209 offset:124
	s_setprio 0
	v_mov_b32_e32 v216, 0xff800000
	v_add_f32_e32 v3, v96, v3
	v_cndmask_b32_e64 v2, v216, v3, s[64:65]
	v_add_f32_e32 v234, v92, v234
	v_cndmask_b32_e64 v0, v216, v234, s[90:91]
	v_add_f32_e32 v235, v97, v235
	v_cndmask_b32_e64 v96, v216, v235, s[74:75]
	v_add_f32_e32 v248, v93, v248
	v_cndmask_b32_e64 v92, v216, v248, s[96:97]
	v_add_f32_e32 v249, v98, v249
	v_cndmask_b32_e64 v97, v216, v249, s[8:9]
	v_add_f32_e32 v250, v94, v250
	v_cndmask_b32_e64 v93, v216, v250, s[86:87]
	v_add_f32_e32 v251, v99, v251
	v_cndmask_b32_e64 v98, v216, v251, s[60:61]
	v_add_f32_e32 v219, v95, v219
	v_cndmask_b32_e64 v94, v216, v219, s[52:53]
	s_waitcnt lgkmcnt(0)
; #define LAS __attribute__((address_space(3)))
; __device__ __forceinline__ unsigned pk_bf16(float lo, float hi) { unsigned r; asm volatile("v_cvt_pk_bf16_f32 %0, %1, %2" : "=v"(r) : "v"(lo), "v"(hi)); return r; }
; template <int ND> ...
;     ...
;     if (loc) {
; #pragma unroll
;         for (int g = 0; g < ND; ++g)
; #pragma unroll
;             for (int i = 0; i < 4; ++i) {
;                 const int ck0 = cst + fq * 4 + i, ck1 = ck0 + 16;
;                 const int rel0 = min(max(ck0 - cq + 15, 0), 30), rel1 = min(max(ck1 - cq + 15, 0), 30);
;                 const bool v0 = (ck0 >= c0w) && (ck0 < c0w + 16), v1 = (ck1 >= c0w) && (ck1 < c0w + 16);
;                 sc[2 * g][i] = v0 ? sc[2 * g][i] + rpb[dr[g] * 31 + rel0] : -INFINITY;
;                 sc[2 * g + 1][i] = v1 ? sc[2 * g + 1][i] + rpb[dr[g] * 31 + rel1] : -INFINITY; }
;     }
;     float mx = -INFINITY;
; #pragma unroll
;     for (int u = 0; u < 2 * ND; ++u) mx = fmaxf(mx, fmaxf(fmaxf(sc[u][0], sc[u][1]), fmaxf(sc[u][2], sc[u][3])));
;     mx = xmax16(mx); mx = xmax32(mx);
;     const float m_new = fmaxf(m_run, mx);
;     const float m_use = (m_new == -INFINITY) ? 0.f : m_new;
;     const float alpha = __builtin_amdgcn_exp2f(m_run - m_use);
;     float ps_sum = 0.f; bf16x8 pf[ND];
; #pragma unroll
;     for (int g = 0; g < ND; ++g) { float pv[8];
; #pragma unroll
;         for (int i = 0; i < 4; ++i) { pv[i] = __builtin_amdgcn_exp2f(sc[2 * g][i] - m_use); pv[4 + i] = __builtin_amdgcn_exp2f(sc[2 * g + 1][i] - m_use); ps_sum += pv[i] + pv[4 + i]; }
;         u32x4 pw; pw.x = pk_bf16(pv[0], pv[1]); pw.y = pk_bf16(pv[2], pv[3]); pw.z = pk_bf16(pv[4], pv[5]); pw.w = pk_bf16(pv[6], pv[7]);
;         pf[g] = as_bf8(pw); }
;     l_run = l_run * alpha + ps_sum; m_run = m_new;
;     __builtin_amdgcn_s_setprio(1);
; #pragma unroll
;     for (int d = 0; d < 4; ++d) { O[d] = O[d] * alpha;
; #pragma unroll
;         for (int g = 0; g < ND; ++g) {
;             const u32x2 va = *(const LAS u32x2*)(lds + vbase + (d * 16 + fr) * vstr + (key0[g] + fq * 4) * 2);
;             const u32x2 vb = *(const LAS u32x2*)(lds + vbase + (d * 16 + fr) * vstr + (key0[g] + 16 + fq * 4) * 2);
;             u32x4 vw; vw.x = va.x; vw.y = va.y; vw.z = vb.x; vw.w = vb.y;
;             O[d] = mfma16(as_bf8(vw), pf[g], O[d]); } }
	v_add_f32_e32 v198, v84, v198
	v_cndmask_b32_e64 v99, v216, v198, s[64:65]
	v_add_f32_e32 v199, v88, v199
	v_cndmask_b32_e64 v95, v216, v199, s[90:91]
	v_add_f32_e32 v200, v85, v200
	v_cndmask_b32_e64 v88, v216, v200, s[74:75]
	v_add_f32_e32 v201, v89, v201
	v_cndmask_b32_e64 v84, v216, v201, s[96:97]
	v_add_f32_e32 v212, v86, v212
	v_cndmask_b32_e64 v212, v216, v212, s[8:9]
	v_add_f32_e32 v213, v90, v213
	v_cndmask_b32_e64 v85, v216, v213, s[86:87]
	v_add_f32_e32 v214, v87, v214
	v_cndmask_b32_e64 v90, v216, v214, s[60:61]
	v_add_f32_e32 v215, v91, v215
	v_cndmask_b32_e64 v86, v216, v215, s[52:53]
	v_add_u32_e32 v219, 0xb000, v190
	v_add_u32_e32 v234, 0xd800, v190
	v_add_u32_e32 v235, 0x10600, v190
	ds_read2_b64 v[220:223], v219 offset0:128 offset1:132
	ds_read2_b64 v[224:227], v234 offset0:160 offset1:164
	ds_read2_b64 v[248:251], v235 offset1:4
	v_max_f32_e32 v3, v98, v98
	v_max_f32_e32 v87, v97, v97
	v_max_f32_e32 v3, v87, v3
	v_max_f32_e32 v87, v94, v94
	v_max_f32_e32 v89, v93, v93
	v_max_f32_e32 v87, v89, v87
	v_max3_f32 v3, v2, v96, v3
	v_max3_f32 v87, v0, v92, v87
	v_max3_f32 v3, v3, s71, v87
	v_max_f32_e32 v87, v90, v90
	v_max_f32_e32 v89, v212, v212
	v_max_f32_e32 v87, v89, v87
	v_max_f32_e32 v89, v86, v86
	v_max_f32_e32 v91, v85, v85
	v_max_f32_e32 v89, v91, v89
	v_max3_f32 v87, v99, v88, v87
	v_max3_f32 v89, v95, v84, v89
	v_max3_f32 v3, v3, v87, v89
	v_mov_b32_e32 v87, v3
	s_nop 1
	v_permlane16_swap_b32_e32 v3, v87
	v_max_f32_e32 v87, v87, v87
	v_max_f32_e32 v3, v3, v3
	v_max_f32_e32 v3, v3, v87
	v_mov_b32_e32 v87, v3
	s_nop 1
	v_permlane32_swap_b32_e32 v3, v87
	v_max3_f32 v3, v188, v3, v87
	v_cmp_neq_f32_e32 vcc, s71, v3
	s_nop 1
	v_cndmask_b32_e32 v87, 0, v3, vcc
	v_sub_f32_e32 v2, v2, v87
	v_sub_f32_e32 v0, v0, v87
	v_exp_f32_e32 v2, v2
	v_exp_f32_e32 v91, v0
	v_sub_f32_e32 v0, v96, v87
	v_sub_f32_e32 v89, v92, v87
	v_exp_f32_e32 v0, v0
	v_exp_f32_e32 v198, v89
	v_add_f32_e32 v199, v91, v2
	v_sub_f32_e32 v92, v93, v87
	v_sub_f32_e32 v89, v97, v87
	v_pk_add_f32 v[200:201], v[198:199], v[0:1]
	v_exp_f32_e32 v199, v92
	v_pk_add_f32 v[200:201], v[200:201], v[200:201] op_sel_hi:[0,1]
	v_sub_f32_e32 v92, v98, v87
	v_exp_f32_e32 v89, v89
	v_exp_f32_e32 v200, v92
	v_sub_f32_e32 v92, v94, v87
	v_exp_f32_e32 v92, v92
	v_add_f32_e32 v93, v199, v89
	v_sub_f32_e32 v94, v95, v87
	v_exp_f32_e32 v204, v94
	v_pk_add_f32 v[96:97], v[92:93], v[200:201]
	v_sub_f32_e32 v93, v99, v87
	v_pk_add_f32 v[96:97], v[96:97], v[96:97] op_sel_hi:[0,1]
	v_exp_f32_e32 v93, v93
	v_sub_f32_e32 v88, v88, v87
	v_sub_f32_e32 v84, v84, v87
	v_exp_f32_e32 v96, v88
	v_exp_f32_e32 v94, v84
	v_cvt_pk_bf16_f32 v88, v2, v0
	v_add_f32_e32 v95, v204, v93
	v_sub_f32_e32 v0, v212, v87
	v_pk_add_f32 v[98:99], v[94:95], v[96:97]
	v_exp_f32_e32 v95, v0
	v_sub_f32_e32 v0, v85, v87
	v_pk_add_f32 v[98:99], v[98:99], v[98:99] op_sel_hi:[0,1]
	v_exp_f32_e32 v97, v0
	v_sub_f32_e32 v0, v90, v87
	v_exp_f32_e32 v98, v0
	v_sub_f32_e32 v0, v86, v87
	v_cvt_pk_bf16_f32 v89, v89, v200
	v_exp_f32_e32 v200, v0
	v_sub_f32_e32 v188, v188, v87
	v_exp_f32_e32 v0, v188
	v_add_f32_e32 v201, v97, v95
	v_pk_add_f32 v[84:85], v[200:201], v[98:99]
	v_cvt_pk_bf16_f32 v90, v91, v198
	v_cvt_pk_bf16_f32 v91, v199, v92
	s_nop 0
	v_add_f32_e32 v2, v84, v85
	v_fmac_f32_e32 v2, v189, v0
	v_cvt_pk_bf16_f32 v84, v93, v96
	v_cvt_pk_bf16_f32 v85, v95, v98
	v_cvt_pk_bf16_f32 v86, v204, v94
	v_cvt_pk_bf16_f32 v87, v97, v200
	s_setprio 1
	v_add_u32_e32 v216, 0x12f00, v190
	ds_read2_b64 v[92:95], v216 offset1:4
	ds_read2_b64 v[96:99], v219 offset0:144 offset1:148
	ds_read2_b64 v[198:201], v234 offset0:176 offset1:180
	ds_read2_b64 v[212:215], v235 offset0:16 offset1:20
	v_pk_mul_f32 v[68:69], v[68:69], v[0:1] op_sel_hi:[1,0]
	v_pk_mul_f32 v[70:71], v[70:71], v[0:1] op_sel_hi:[1,0]
	v_pk_mul_f32 v[80:81], v[80:81], v[0:1] op_sel_hi:[1,0]
	v_pk_mul_f32 v[82:83], v[82:83], v[0:1] op_sel_hi:[1,0]
	v_pk_mul_f32 v[72:73], v[72:73], v[0:1] op_sel_hi:[1,0]
	v_pk_mul_f32 v[74:75], v[74:75], v[0:1] op_sel_hi:[1,0]
	v_pk_mul_f32 v[76:77], v[76:77], v[0:1] op_sel_hi:[1,0]
	v_pk_mul_f32 v[78:79], v[78:79], v[0:1] op_sel_hi:[1,0]
	s_waitcnt lgkmcnt(4)
	v_mfma_f32_16x16x32_bf16 v[68:71], v[220:223], v[88:91], v[68:71]
	v_mfma_f32_16x16x32_bf16 v[80:83], v[224:227], v[88:91], v[80:83]
	v_mfma_f32_16x16x32_bf16 v[72:75], v[248:251], v[88:91], v[72:75]
	ds_read2_b64 v[220:223], v216 offset0:16 offset1:20
	s_waitcnt lgkmcnt(4)
	v_mfma_f32_16x16x32_bf16 v[76:79], v[92:95], v[88:91], v[76:79]
	s_waitcnt lgkmcnt(3)
	v_mfma_f32_16x16x32_bf16 v[68:71], v[96:99], v[84:87], v[68:71]
	s_waitcnt lgkmcnt(2)
	v_mfma_f32_16x16x32_bf16 v[80:83], v[198:201], v[84:87], v[80:83]
	s_waitcnt lgkmcnt(1)
	v_mfma_f32_16x16x32_bf16 v[72:75], v[212:215], v[84:87], v[72:75]
	s_waitcnt lgkmcnt(0)
	v_mfma_f32_16x16x32_bf16 v[76:79], v[220:223], v[84:87], v[76:79]
	s_setprio 0
	s_add_i32 s47, s47, 2
	v_add_u32_e32 v190, 0x100, v190
	v_add_u32_e32 v191, 0x4800, v191
	v_add_u32_e32 v192, 0xf8, v192
	v_add_u32_e32 v193, 0xf8, v193
	v_add_u32_e32 v194, 0xf8, v194
	v_add_u32_e32 v195, 0xf8, v195
	v_add_u32_e32 v206, 0xf8, v206
	v_add_u32_e32 v207, 0xf8, v207
	v_add_u32_e32 v208, 0xf8, v208
	v_add_u32_e32 v209, 0xf8, v209
	v_add_u32_e32 v210, 0x4800, v210
	s_cmp_lt_i32 s47, s46
	v_add_u32_e32 v211, 0x100, v211
	s_cbranch_scc0 .LBB0_810
	v_mov_b32_e32 v188, v3
	v_mov_b32_e32 v189, v2
	s_branch .LBB0_775
